# res_fix phases 9/12/17 hand-written (one wave per sample row, all loads issued together, 8-byte bf16 stores) instead of the compiled serialized version
# speedup vs baseline: 1.0021x; 1.0021x over previous
; __device__ __forceinline__ void res_fix_phase(const Params& p) {
;   u16* xb = (u16*)(p.ws + O_XB);
;   float* part = (float*)(p.ws + O_PART);
;   const int lane = threadIdx.x & 63, wave = threadIdx.x >> 6;
;   for (int row = NP + blockIdx.x * 8 + wave; row < MT; row += gridDim.x * 8) {
;     const float* xr = p.out + (size_t)row * 1024;
;     float ss = 0.f;
; #pragma unroll
;     for (int i = 0; i < 4; i++) {
;       float4 v = *(const float4*)(xr + i * 256 + lane * 4);
;       ss += v.x * v.x + v.y * v.y + v.z * v.z + v.w * v.w;
;       ushort4 o;
;       o.x = f2bf(v.x); o.y = f2bf(v.y); o.z = f2bf(v.z); o.w = f2bf(v.w);
;       *(ushort4*)(xb + (size_t)row * 1024 + i * 256 + lane * 4) = o;
;     }
;     ss = wsum64(ss);
;     if (lane < 16) part[(size_t)row * 16 + lane] = (lane == 0) ? ss : 0.f;
;   }
; }
.LBB0_1239:
	v_lshrrev_b32_e32 v154, 6, v128
	v_and_b32_e32 v153, 63, v128
	v_readlane_b32 s1, v254, 0
	v_readfirstlane_b32 s0, v154
	s_nop 3
	s_lshl_b32 s1, s1, 3
	s_add_u32 s2, s1, s0
	s_cmp_ge_u32 s2, 512
	s_cbranch_scc1 .Lrf_done_9
	v_lshlrev_b32_e32 v150, 4, v153
	v_lshlrev_b32_e32 v151, 3, v153
	v_lshlrev_b32_e32 v152, 2, v153
	v_cmp_eq_u32_e64 s[20:21], 0, v153
	v_cmp_gt_u32_e64 s[22:23], 16, v153
	s_lshl_b32 s3, s2, 12
	s_add_u32 s8, s94, 0x4000000
	s_addc_u32 s9, s95, 0
	s_add_u32 s8, s8, s3
	s_addc_u32 s9, s9, 0
	s_add_u32 s10, s96, 0xd408100
	s_addc_u32 s11, s97, 0
	s_add_u32 s10, s10, s3
	s_addc_u32 s11, s11, 0
	global_load_dwordx4 v[2:5], v150, s[8:9]
	global_load_dwordx4 v[6:9], v150, s[8:9] offset:1024
	global_load_dwordx4 v[10:13], v150, s[8:9] offset:2048
	global_load_dwordx4 v[14:17], v150, s[8:9] offset:3072
	s_waitcnt vmcnt(0)
	v_mul_f32_e32 v154, v2, v2
	v_fmac_f32_e32 v154, v3, v3
	v_fmac_f32_e32 v154, v4, v4
	v_fmac_f32_e32 v154, v5, v5
	v_fmac_f32_e32 v154, v6, v6
	v_fmac_f32_e32 v154, v7, v7
	v_fmac_f32_e32 v154, v8, v8
	v_fmac_f32_e32 v154, v9, v9
	v_fmac_f32_e32 v154, v10, v10
	v_fmac_f32_e32 v154, v11, v11
	v_fmac_f32_e32 v154, v12, v12
	v_fmac_f32_e32 v154, v13, v13
	v_fmac_f32_e32 v154, v14, v14
	v_fmac_f32_e32 v154, v15, v15
	v_fmac_f32_e32 v154, v16, v16
	v_fmac_f32_e32 v154, v17, v17
	s_add_u32 s3, s2, 16384
	s_lshl_b32 s12, s3, 11
	s_add_u32 s14, s96, 0x2f08100
	s_addc_u32 s15, s97, 0
	s_add_u32 s14, s14, s12
	s_addc_u32 s15, s15, 0
	v_cvt_pk_bf16_f32 v156, v2, v3
	v_cvt_pk_bf16_f32 v157, v4, v5
	v_cvt_pk_bf16_f32 v158, v6, v7
	v_cvt_pk_bf16_f32 v159, v8, v9
	v_cvt_pk_bf16_f32 v160, v10, v11
	v_cvt_pk_bf16_f32 v161, v12, v13
	v_cvt_pk_bf16_f32 v162, v14, v15
	v_cvt_pk_bf16_f32 v163, v16, v17
	global_store_dwordx2 v151, v[156:157], s[14:15]
	global_store_dwordx2 v151, v[158:159], s[14:15] offset:512
	global_store_dwordx2 v151, v[160:161], s[14:15] offset:1024
	global_store_dwordx2 v151, v[162:163], s[14:15] offset:1536
	v_add_f32_dpp v154, v154, v154 quad_perm:[1,0,3,2] row_mask:0xf bank_mask:0xf
	s_nop 1
	v_add_f32_dpp v154, v154, v154 quad_perm:[2,3,0,1] row_mask:0xf bank_mask:0xf
	s_nop 1
	v_add_f32_dpp v154, v154, v154 row_half_mirror row_mask:0xf bank_mask:0xf
	s_nop 1
	v_add_f32_dpp v154, v154, v154 row_mirror row_mask:0xf bank_mask:0xf
	v_mov_b32_e32 v155, v154
	s_nop 1
	v_permlane16_swap_b32_e32 v155, v154
	v_add_f32_e32 v154, v154, v155
	v_mov_b32_e32 v155, v154
	s_nop 1
	v_permlane32_swap_b32_e32 v155, v154
	v_add_f32_e32 v154, v154, v155
	v_cndmask_b32_e64 v155, 0, v154, s[20:21]
	s_lshl_b32 s12, s3, 6
	s_add_u32 s14, s96, 0x2e00100
	s_addc_u32 s15, s97, 0
	s_add_u32 s14, s14, s12
	s_addc_u32 s15, s15, 0
	s_mov_b64 s[16:17], exec
	s_mov_b64 exec, s[22:23]
	s_nop 1
	global_store_dword v152, v155, s[14:15]
	s_mov_b64 exec, s[16:17]
